# additionally the diff, stick-breaking, GLU and S5 loop heads aligned to 64 bytes
# baseline (speedup 1.0000x reference)
.LBB0_449:
	v_lshrrev_b32_e32 v16, 1, v8
	v_and_b32_e32 v139, 24, v16
	v_and_b32_e32 v15, 15, v8
	v_lshlrev_b32_e32 v16, 1, v139
	v_lshlrev_b32_e32 v8, 2, v8
	v_lshl_or_b32 v138, s34, 6, v15
	v_lshl_or_b32 v15, v15, 6, v16
	s_lshl_b32 s36, s36, 5
	v_and_b32_e32 v8, 32, v8
	s_lshl_b32 s34, s34, 13
	v_bitop3_b32 v16, v15, s34, v8 bitop3:0xde
	s_and_b32 s34, s36, 0x60
	s_lshl_b32 s36, s34, 7
	s_add_i32 m0, s18, 0x18000
	v_lshl_add_u64 v[6:7], v[6:7], 0, s[84:85]
	v_bitop3_b32 v140, v15, s36, v8 bitop3:0xde
	s_waitcnt vmcnt(2)
	s_barrier
	global_load_lds_dwordx4 v[6:7], off
	v_lshl_add_u64 v[4:5], v[4:5], 0, s[84:85]
	s_add_i32 m0, s18, 0x1a000
	s_add_i32 s36, s18, 0x8000
	s_add_i32 s37, s18, 0xa000
	global_load_lds_dwordx4 v[4:5], off
	v_lshl_add_u64 v[2:3], v[2:3], 0, s[84:85]
	s_mov_b32 m0, s36
	s_add_u32 s38, s20, 0x20080
	global_load_lds_dwordx4 v[2:3], off
	v_lshl_add_u64 v[0:1], v[0:1], 0, s[84:85]
	s_mov_b32 m0, s37
	s_addc_u32 s39, s21, 0
	global_load_lds_dwordx4 v[0:1], off
	s_add_i32 m0, s18, 0x1c000
	v_lshl_add_u64 v[0:1], s[38:39], 0, v[192:193]
	global_load_lds_dwordx4 v[0:1], off
	v_lshl_add_u64 v[0:1], s[38:39], 0, v[132:133]
	s_add_i32 m0, s18, 0x1e000
	s_add_u32 s38, s24, s26
	global_load_lds_dwordx4 v[0:1], off
	v_lshlrev_b32_e32 v0, 13, v9
	v_and_b32_e32 v0, 0xffffc000, v0
	s_addc_u32 s39, s25, s27
	v_lshl_add_u32 v0, v10, 10, v0
	v_and_b32_e32 v1, 1, v9
	v_lshl_or_b32 v0, v1, 6, v0
	s_add_u32 s24, s38, 0x22a20080
	v_lshl_add_u32 v0, v11, 1, v0
	v_mov_b32_e32 v1, v193
	s_addc_u32 s25, s39, 0
	v_lshl_add_u64 v[134:135], s[24:25], 0, v[0:1]
	v_lshlrev_b32_e32 v0, 13, v12
	v_and_b32_e32 v0, 0xffffc000, v0
	s_add_u32 s22, s22, s78
	v_lshl_add_u32 v0, v13, 10, v0
	v_and_b32_e32 v1, 1, v12
	s_addc_u32 s23, s23, 0
	v_lshl_or_b32 v0, v1, 6, v0
	s_add_u32 s22, s22, s40
	s_waitcnt vmcnt(6)
	v_lshl_add_u32 v0, v14, 1, v0
	v_mov_b32_e32 v1, v193
	s_addc_u32 s23, s23, 0
	v_lshl_add_u64 v[136:137], s[24:25], 0, v[0:1]
	s_add_u32 s40, s22, 0x5f00100
	v_mov_b32_e32 v0, 0
	s_addc_u32 s41, s23, 0
	s_mov_b32 s42, -2
	s_mov_b64 s[22:23], 0
	v_add_u32_e32 v141, 0, v16
	v_mov_b32_e32 v1, v0
	v_mov_b32_e32 v2, v0
	v_mov_b32_e32 v3, v0
	v_mov_b32_e32 v4, v0
	v_mov_b32_e32 v5, v0
	v_mov_b32_e32 v6, v0
	v_mov_b32_e32 v7, v0
	v_mov_b32_e32 v16, v0
	v_mov_b32_e32 v17, v0
	v_mov_b32_e32 v18, v0
	v_mov_b32_e32 v19, v0
	v_mov_b32_e32 v20, v0
	v_mov_b32_e32 v21, v0
	v_mov_b32_e32 v22, v0
	v_mov_b32_e32 v23, v0
	v_mov_b32_e32 v32, v0
	v_mov_b32_e32 v33, v0
	v_mov_b32_e32 v34, v0
	v_mov_b32_e32 v35, v0
	v_mov_b32_e32 v36, v0
	v_mov_b32_e32 v37, v0
	v_mov_b32_e32 v38, v0
	v_mov_b32_e32 v39, v0
	v_mov_b32_e32 v48, v0
	v_mov_b32_e32 v49, v0
	v_mov_b32_e32 v50, v0
	v_mov_b32_e32 v51, v0
	v_mov_b32_e32 v52, v0
	v_mov_b32_e32 v53, v0
	v_mov_b32_e32 v54, v0
	v_mov_b32_e32 v55, v0
	v_mov_b32_e32 v8, v0
	v_mov_b32_e32 v9, v0
	v_mov_b32_e32 v10, v0
	v_mov_b32_e32 v11, v0
	v_mov_b32_e32 v12, v0
	v_mov_b32_e32 v13, v0
	v_mov_b32_e32 v14, v0
	v_mov_b32_e32 v15, v0
	v_mov_b32_e32 v24, v0
	v_mov_b32_e32 v25, v0
	v_mov_b32_e32 v26, v0
	v_mov_b32_e32 v27, v0
	v_mov_b32_e32 v28, v0
	v_mov_b32_e32 v29, v0
	v_mov_b32_e32 v30, v0
	v_mov_b32_e32 v31, v0
	v_mov_b32_e32 v40, v0
	v_mov_b32_e32 v41, v0
	v_mov_b32_e32 v42, v0
	v_mov_b32_e32 v43, v0
	v_mov_b32_e32 v44, v0
	v_mov_b32_e32 v45, v0
	v_mov_b32_e32 v46, v0
	v_mov_b32_e32 v47, v0
	v_mov_b32_e32 v56, v0
	v_mov_b32_e32 v57, v0
	v_mov_b32_e32 v58, v0
	v_mov_b32_e32 v59, v0
	v_mov_b32_e32 v60, v0
	v_mov_b32_e32 v61, v0
	v_mov_b32_e32 v62, v0
	v_mov_b32_e32 v63, v0
	v_mov_b32_e32 v64, v0
	v_mov_b32_e32 v65, v0
	v_mov_b32_e32 v66, v0
	v_mov_b32_e32 v67, v0
	v_mov_b32_e32 v68, v0
	v_mov_b32_e32 v69, v0
	v_mov_b32_e32 v70, v0
	v_mov_b32_e32 v71, v0
	v_mov_b32_e32 v80, v0
	v_mov_b32_e32 v81, v0
	v_mov_b32_e32 v82, v0
	v_mov_b32_e32 v83, v0
	v_mov_b32_e32 v84, v0
	v_mov_b32_e32 v85, v0
	v_mov_b32_e32 v86, v0
	v_mov_b32_e32 v87, v0
	v_mov_b32_e32 v96, v0
	v_mov_b32_e32 v97, v0
	v_mov_b32_e32 v98, v0
	v_mov_b32_e32 v99, v0
	v_mov_b32_e32 v100, v0
	v_mov_b32_e32 v101, v0
	v_mov_b32_e32 v102, v0
	v_mov_b32_e32 v103, v0
	v_mov_b32_e32 v112, v0
	v_mov_b32_e32 v113, v0
	s_waitcnt vmcnt(0)
	v_mov_b32_e32 v114, v0
	v_mov_b32_e32 v115, v0
	v_mov_b32_e32 v116, v0
	v_mov_b32_e32 v117, v0
	v_mov_b32_e32 v118, v0
	v_mov_b32_e32 v119, v0
	v_mov_b32_e32 v72, v0
	v_mov_b32_e32 v73, v0
	v_mov_b32_e32 v74, v0
	v_mov_b32_e32 v75, v0
	v_mov_b32_e32 v76, v0
	v_mov_b32_e32 v77, v0
	v_mov_b32_e32 v78, v0
	v_mov_b32_e32 v79, v0
	v_mov_b32_e32 v88, v0
	v_mov_b32_e32 v89, v0
	v_mov_b32_e32 v90, v0
	v_mov_b32_e32 v91, v0
	v_mov_b32_e32 v92, v0
	v_mov_b32_e32 v93, v0
	v_mov_b32_e32 v94, v0
	v_mov_b32_e32 v95, v0
	v_mov_b32_e32 v104, v0
	v_mov_b32_e32 v105, v0
	v_mov_b32_e32 v106, v0
	v_mov_b32_e32 v107, v0
	v_mov_b32_e32 v108, v0
	v_mov_b32_e32 v109, v0
	v_mov_b32_e32 v110, v0
	v_mov_b32_e32 v111, v0
	v_mov_b32_e32 v120, v0
	v_mov_b32_e32 v121, v0
	v_mov_b32_e32 v122, v0
	v_mov_b32_e32 v123, v0
	v_mov_b32_e32 v124, v0
	v_mov_b32_e32 v125, v0
	v_mov_b32_e32 v126, v0
	v_mov_b32_e32 v127, v0
	s_barrier
	.p2align 6

.LBB0_459:
	s_and_b64 vcc, exec, s[16:17]
	s_cbranch_vccnz .LBB0_470
	.p2align 6

.LBB0_500:
	s_add_i32 s22, s22, 4
	s_cmp_eq_u32 s15, 8
	s_cbranch_scc1 .LBB0_503
	.p2align 6

.LBB0_510:
	s_add_i32 s15, s15, 4
	s_cmp_eq_u32 s18, 8
	s_cbranch_scc1 .LBB0_515
	.p2align 6

.LBB0_527:
	s_sub_i32 s27, s27, 64
	s_add_i32 s28, s28, 64
	s_cmp_eq_u32 s24, s29
	s_cbranch_scc1 .LBB0_604
	.p2align 6
